# v7 + grid barrier: leader releases the local workgroups (XGEN atomic) before its own L1 invalidate; redundant vmcnt(0) before buffer_inv dropped in both paths
# baseline (speedup 1.0000x reference)
.LBB0_603:
	s_or_b64 exec, exec, s[8:9]
	buffer_inv sc1
	s_waitcnt vmcnt(0)

.LBB0_621:
	s_or_b64 exec, exec, s[6:7]
	s_mov_b64 s[6:7], exec
	v_mbcnt_lo_u32_b32 v0, s6, 0
	v_mbcnt_hi_u32_b32 v0, s7, v0
	v_cmp_eq_u32_e32 vcc, 0, v0
	s_and_saveexec_b64 s[8:9], vcc
	s_cbranch_execz .LBB0_623
	s_bcnt1_i32_b64 s3, s[6:7]
	v_mov_b32_e32 v0, 0x2000
	v_mov_b32_e32 v1, s3
	global_atomic_add v0, v1, s[4:5] offset:1024

.LBB0_761:
	s_or_b64 exec, exec, s[10:11]
	buffer_inv sc1
	s_waitcnt vmcnt(0)

.LBB0_779:
	s_or_b64 exec, exec, s[8:9]
	s_mov_b64 s[8:9], exec
	v_mbcnt_lo_u32_b32 v0, s8, 0
	v_mbcnt_hi_u32_b32 v0, s9, v0
	v_cmp_eq_u32_e32 vcc, 0, v0
	s_and_saveexec_b64 s[10:11], vcc
	s_cbranch_execz .LBB0_781
	s_bcnt1_i32_b64 s3, s[8:9]
	v_mov_b32_e32 v0, 0x2000
	v_mov_b32_e32 v1, s3
	global_atomic_add v0, v1, s[6:7] offset:1024

.LBB0_1034:
	s_or_b64 exec, exec, s[12:13]
	buffer_inv sc1
	s_waitcnt vmcnt(0)

.LBB0_1052:
	s_or_b64 exec, exec, s[8:9]
	s_mov_b64 s[8:9], exec
	v_mbcnt_lo_u32_b32 v0, s8, 0
	v_mbcnt_hi_u32_b32 v0, s9, v0
	v_cmp_eq_u32_e32 vcc, 0, v0
	s_and_saveexec_b64 s[12:13], vcc
	s_cbranch_execz .LBB0_1054
	s_bcnt1_i32_b64 s3, s[8:9]
	v_mov_b32_e32 v0, 0x2000
	v_mov_b32_e32 v1, s3
	global_atomic_add v0, v1, s[6:7] offset:1024
